# out-proj residual loads and mixer conv-state/KV loads without the nt hint on the all-to-all release version
# baseline (speedup 1.0000x reference)
; #define LAS __attribute__((address_space(3)))
; __device__ __forceinline__ void attn_sample_item(const Args& a, int l, int n, LAS unsigned char* lds, int tid, int lane, int wave) {
;     ...
; #pragma unroll
;     for (int pass = 0; pass < 4; ++pass) {
;         const int r = pass * 32 + (tid >> 4);
;         kc[pass][0] = __builtin_nontemporal_load((const f32x4*)(ck + r * 128 + c16 * 8)); kc[pass][1] = __builtin_nontemporal_load((const f32x4*)(ck + r * 128 + c16 * 8 + 4));
;         vc[pass][0] = __builtin_nontemporal_load((const f32x4*)(cv + r * 128 + c16 * 8)); vc[pass][1] = __builtin_nontemporal_load((const f32x4*)(cv + r * 128 + c16 * 8 + 4));
;     }
; #pragma unroll
;     for (int pass = 0; pass < 4; ++pass) {
;         const int r = pass * 32 + (tid >> 4);
;         const f32x4 k0 = kc[pass][0], k1 = kc[pass][1], v0 = vc[pass][0], v1 = vc[pass][1];
;         u32x4 kw; kw.x = pk_bf16(k0.x, k0.y); kw.y = pk_bf16(k0.z, k0.w); kw.z = pk_bf16(k1.x, k1.y); kw.w = pk_bf16(k1.z, k1.w);
;         u32x4 vw; vw.x = pk_bf16(v0.x, v0.y); vw.y = pk_bf16(v0.z, v0.w); vw.z = pk_bf16(v1.x, v1.y); vw.w = pk_bf16(v1.z, v1.w);
;         *(LAS u32x4*)(lds + kvh * KH + r * 144 + sub * 16) = kw;
;         *(LAS u32x4*)(lds + VOFF + kvh * 2 * VH + (sub >> 2) * VH + r * 64 + (sub & 3) * 16) = vw;
;         if (r >= 8) { float* pk = oks + (r - 8) * 128 + c16 * 8; float* pv = ovs + (r - 8) * 128 + c16 * 8;
;             __builtin_nontemporal_store(k0, (f32x4*)pk); __builtin_nontemporal_store(k1, (f32x4*)(pk + 4)); __builtin_nontemporal_store(v0, (f32x4*)pv); __builtin_nontemporal_store(v1, (f32x4*)(pv + 4)); }
.LBB0_506:
	v_readlane_b32 s0, v255, 23
	s_add_i32 s4, s36, s0
	s_ashr_i32 s5, s4, 31
	s_lshl_b64 s[18:19], s[4:5], 16
	v_readlane_b32 s0, v253, 4
	v_readlane_b32 s6, v253, 10
	v_readlane_b32 s10, v253, 14
	v_readlane_b32 s7, v253, 11
	v_readlane_b32 s11, v253, 15
	s_add_u32 s6, s10, s18
	v_readlane_b32 s8, v253, 12
	v_readlane_b32 s12, v253, 16
	s_addc_u32 s7, s11, s19
	v_lshlrev_b32_e32 v16, 3, v130
	v_readlane_b32 s9, v253, 13
	v_readlane_b32 s13, v253, 17
	s_add_u32 s8, s12, s18
	v_and_b32_e32 v97, 15, v130
	v_and_b32_e32 v16, 0xffffff80, v16
	s_addc_u32 s9, s13, s19
	v_lshlrev_b32_e32 v172, 5, v97
	v_ashrrev_i32_e32 v17, 31, v16
	v_lshl_add_u64 v[18:19], s[6:7], 0, v[172:173]
	v_lshl_add_u64 v[20:21], s[8:9], 0, v[172:173]
	v_lshlrev_b64 v[22:23], 2, v[16:17]
	v_lshl_add_u64 v[24:25], v[18:19], 0, v[22:23]
	v_lshl_add_u64 v[22:23], v[20:21], 0, v[22:23]
	global_load_dwordx4 v[64:67], v[24:25], off offset:16
	global_load_dwordx4 v[72:75], v[24:25], off
	global_load_dwordx4 v[68:71], v[22:23], off offset:16
	global_load_dwordx4 v[76:79], v[22:23], off
	v_add_u32_e32 v22, 0x1000, v16
	v_ashrrev_i32_e32 v23, 31, v22
	v_lshlrev_b64 v[22:23], 2, v[22:23]
	v_lshl_add_u64 v[24:25], v[18:19], 0, v[22:23]
	v_lshl_add_u64 v[22:23], v[20:21], 0, v[22:23]
	global_load_dwordx4 v[48:51], v[24:25], off offset:16
	global_load_dwordx4 v[56:59], v[24:25], off
	global_load_dwordx4 v[52:55], v[22:23], off offset:16
	global_load_dwordx4 v[60:63], v[22:23], off
	v_add_u32_e32 v22, 0x2000, v16
	v_ashrrev_i32_e32 v23, 31, v22
	v_lshlrev_b64 v[22:23], 2, v[22:23]
	v_add_u32_e32 v16, 0x3000, v16
	v_lshl_add_u64 v[24:25], v[18:19], 0, v[22:23]
	v_lshl_add_u64 v[22:23], v[20:21], 0, v[22:23]
	v_ashrrev_i32_e32 v17, 31, v16
	global_load_dwordx4 v[32:35], v[24:25], off offset:16
	global_load_dwordx4 v[40:43], v[24:25], off
	global_load_dwordx4 v[36:39], v[22:23], off offset:16
	global_load_dwordx4 v[44:47], v[22:23], off
	v_lshlrev_b64 v[22:23], 2, v[16:17]
	v_lshl_add_u64 v[24:25], v[18:19], 0, v[22:23]
	v_lshl_add_u64 v[28:29], v[20:21], 0, v[22:23]
	global_load_dwordx4 v[16:19], v[24:25], off offset:16
	s_nop 0
	global_load_dwordx4 v[24:27], v[24:25], off
	s_nop 0
	global_load_dwordx4 v[20:23], v[28:29], off offset:16
	s_nop 0
	global_load_dwordx4 v[28:31], v[28:29], off
	v_bfe_u32 v99, v130, 3, 1
	s_movk_i32 s6, 0x5a00
	v_readlane_b32 s0, v254, 18
	v_lshrrev_b32_e32 v101, 2, v107
	v_mad_u32_u24 v110, v99, s6, 0
	s_add_u32 s6, s0, s18
	v_readlane_b32 s0, v254, 19
	v_readlane_b32 s4, v253, 8
	v_ashrrev_i32_e32 v100, 4, v130
	v_lshlrev_b32_e32 v98, 4, v107
	v_lshlrev_b32_e32 v102, 4, v130
	v_mul_i32_i24_e32 v103, 0xfffff600, v99
	v_mul_u32_u24_e32 v104, 0x2800, v101
	s_addc_u32 s7, s0, s19
	v_readlane_b32 s0, v254, 20
	v_readlane_b32 s5, v253, 9
	v_and_b32_e32 v111, 48, v102
	v_mul_lo_u32 v114, v100, s84
	v_add_u32_e32 v101, v110, v98
	v_add3_u32 v112, v110, v103, v104
	s_add_u32 s4, s0, s18
	v_readlane_b32 s0, v254, 21
	v_add_u32_e32 v113, v112, v111
	v_add_u32_e32 v115, v101, v114
	s_addc_u32 s5, s0, s19
	v_lshl_add_u32 v120, v100, 6, v113
	v_lshl_add_u64 v[102:103], s[6:7], 0, v[172:173]
	v_lshl_add_u64 v[104:105], s[4:5], 0, v[172:173]
	v_cmp_lt_i32_e32 vcc, 7, v100
	v_readlane_b32 s1, v253, 5
	v_readlane_b32 s2, v253, 6
	v_readlane_b32 s3, v253, 7
	v_readlane_b32 s14, v253, 18
	v_readlane_b32 s15, v253, 19
	s_waitcnt vmcnt(15)
	v_cvt_pk_bf16_f32 v118, v64, v65
	s_waitcnt vmcnt(14)
	v_cvt_pk_bf16_f32 v116, v72, v73
	v_cvt_pk_bf16_f32 v117, v74, v75
	v_cvt_pk_bf16_f32 v119, v66, v67
	ds_write_b128 v115, v[116:119]
	s_waitcnt vmcnt(12)
	v_cvt_pk_bf16_f32 v116, v76, v77
	v_cvt_pk_bf16_f32 v117, v78, v79
	v_cvt_pk_bf16_f32 v118, v68, v69
	v_cvt_pk_bf16_f32 v119, v70, v71
	ds_write_b128 v120, v[116:119] offset:46080
	s_and_saveexec_b64 s[8:9], vcc
	s_cbranch_execz .LBB0_508
	v_lshl_add_u32 v172, v100, 7, v225
	v_lshlrev_b64 v[116:117], 2, v[172:173]
	v_lshl_add_u64 v[118:119], v[104:105], 0, v[116:117]
	v_lshl_add_u64 v[116:117], v[102:103], 0, v[116:117]
	global_store_dwordx4 v[116:117], v[72:75], off nt
	global_store_dwordx4 v[116:117], v[64:67], off offset:16 nt
	global_store_dwordx4 v[118:119], v[76:79], off nt
	global_store_dwordx4 v[118:119], v[68:71], off offset:16 nt
